# GEMM phase prologue: the second K-tile's six stage loads are issued before the first wait/barrier (vmcnt 2 -> 8), FFN and down/out GEMM instances; on top of v49
# baseline (speedup 1.0000x reference)
.LBB0_283:
	s_lshl_b32 s19, s16, 6
	s_lshl_b32 s20, s16, 13
	s_lshl_b32 s16, s17, 5
	s_and_b32 s22, s16, 0x60
	s_add_i32 m0, s39, 0x18000
	v_lshl_add_u64 v[6:7], v[6:7], 0, s[10:11]
	s_lshl_b32 s23, s22, 7
	global_load_lds_dwordx4 v[6:7], off
	v_lshl_add_u64 v[4:5], v[4:5], 0, s[10:11]
	s_add_i32 m0, s39, 0x1a000
	s_add_i32 s74, s39, 0x8000
	s_add_i32 s75, s39, 0xa000
	global_load_lds_dwordx4 v[4:5], off
	v_lshl_add_u64 v[0:1], v[0:1], 0, s[10:11]
	s_mov_b32 m0, s74
	s_add_u32 s16, s40, 0x40080
	global_load_lds_dwordx4 v[0:1], off
	v_lshl_add_u64 v[0:1], v[2:3], 0, s[10:11]
	s_mov_b32 m0, s75
	s_addc_u32 s17, s41, 0
	global_load_lds_dwordx4 v[0:1], off
	s_add_i32 m0, s39, 0x1c000
	v_lshl_add_u64 v[0:1], s[16:17], 0, v[150:151]
	global_load_lds_dwordx4 v[0:1], off
	v_lshl_add_u64 v[0:1], s[16:17], 0, v[156:157]
	s_add_i32 m0, s39, 0x1e000
	v_lshlrev_b32_e32 v3, 2, v8
	global_load_lds_dwordx4 v[0:1], off
	s_waitcnt vmcnt(8)
	s_barrier
	v_lshrrev_b32_e32 v0, 1, v8
	v_and_b32_e32 v0, 24, v0
	v_and_b32_e32 v1, 15, v8
	v_lshlrev_b32_e32 v2, 1, v0
	v_or_b32_e32 v172, s19, v1
	v_lshl_or_b32 v2, v1, 6, v2
	v_bitop3_b32 v174, s19, v203, v1 bitop3:0xc8
	v_lshlrev_b32_e32 v1, 14, v12
	v_and_b32_e32 v3, 32, v3
	s_cmpk_lt_u32 s18, 0x100
	v_and_b32_e32 v1, 0xffff8000, v1
	v_bitop3_b32 v4, v2, s20, v3 bitop3:0xde
	v_bitop3_b32 v173, v2, s23, v3 bitop3:0xde
	s_cselect_b64 s[16:17], -1, 0
	s_sub_i32 s76, s57, s13
	v_lshl_add_u32 v1, v13, 11, v1
	v_and_b32_e32 v2, 1, v12
	s_add_u32 s18, s4, 0x18200000
	v_readlane_b32 s23, v250, 20
	v_lshl_or_b32 v1, v2, 6, v1
	s_addc_u32 s19, s5, 0
	s_mul_hi_i32 s20, s23, 0x31800
	s_mul_i32 s23, s23, 0x31800
	v_lshl_add_u32 v158, v14, 1, v1
	v_lshlrev_b32_e32 v1, 14, v9
	s_add_u32 s23, s4, s23
	v_and_b32_e32 v1, 0xffff8000, v1
	s_waitcnt vmcnt(6)
	s_addc_u32 s20, s5, s20
	v_lshl_add_u32 v1, v10, 11, v1
	v_and_b32_e32 v2, 1, v9
	s_add_u32 s77, s23, 0x900000
	v_lshl_or_b32 v1, v2, 6, v1
	s_addc_u32 s78, s20, 0
	v_or_b32_e32 v175, s22, v0
	v_mov_b32_e32 v159, v151
	v_lshl_add_u32 v160, v11, 1, v1
	v_mov_b32_e32 v161, v151
	s_mov_b32 s35, 0
	v_add_u32_e32 v176, 0, v4
	s_lshl_b32 s79, s22, 2
	v_lshlrev_b32_e32 v177, 2, v0
	s_mov_b32 s20, 0
	s_barrier
	s_branch .LBB0_286

.LBB0_601:
	s_add_i32 m0, s65, 0x18000
	v_lshl_add_u64 v[0:1], v[0:1], 0, s[10:11]
	global_load_lds_dwordx4 v[0:1], off
	v_lshl_add_u64 v[0:1], v[2:3], 0, s[10:11]
	s_add_i32 m0, s65, 0x1a000
	s_add_i32 s72, s65, 0x8000
	global_load_lds_dwordx4 v[0:1], off
	v_lshl_add_u64 v[0:1], v[8:9], 0, s[10:11]
	s_mov_b32 m0, s72
	s_add_i32 s73, s65, 0xa000
	global_load_lds_dwordx4 v[0:1], off
	v_lshl_add_u64 v[0:1], v[10:11], 0, s[10:11]
	s_mov_b32 m0, s73
	v_bfe_u32 v19, v18, 4, 2
	global_load_lds_dwordx4 v[0:1], off
	s_add_i32 m0, s65, 0x1c000
	v_lshl_add_u64 v[0:1], v[4:5], 0, s[10:11]
	global_load_lds_dwordx4 v[0:1], off
	v_lshl_add_u64 v[0:1], v[6:7], 0, s[10:11]
	s_add_i32 m0, s65, 0x1e000
	v_and_b32_e32 v20, 15, v18
	global_load_lds_dwordx4 v[0:1], off
	s_waitcnt vmcnt(8)
	s_barrier
	v_lshlrev_b32_e32 v22, 4, v19
	v_lshlrev_b32_e32 v18, 2, v18
	s_and_b32 s70, s4, 3
	s_lshr_b32 s74, s17, 6
	v_lshl_or_b32 v210, s5, 6, v20
	v_lshl_or_b32 v20, v20, 6, v22
	s_lshl_b32 s4, s5, 13
	v_and_b32_e32 v18, 32, v18
	v_bitop3_b32 v22, v20, s4, v18 bitop3:0xde
	s_lshl_b32 s4, s70, 12
	s_add_i32 s71, s74, -2
	s_cmpk_lt_u32 s16, 0x100
	s_mul_i32 s75, s49, 3
	s_cselect_b64 s[16:17], -1, 0
	s_add_i32 s75, s75, 2
	v_cndmask_b32_e64 v158, 0.5, 1.0, s[14:15]
	s_add_u32 s14, s60, 0xaa00000
	s_addc_u32 s15, s61, 0
	s_add_u32 s26, s60, 0x13a00000
	s_addc_u32 s27, s61, 0
	s_bitcmp1_b32 s82, 0
	v_bitop3_b32 v211, v20, s4, v18 bitop3:0xde
	s_cselect_b32 s4, 0x240000, 0
	s_add_u32 s4, s60, s4
	s_addc_u32 s5, s61, 0
	s_add_u32 s76, s4, 0xd00000
	s_addc_u32 s77, s5, 0
	s_mul_hi_i32 s4, s48, 0x51000
	s_mul_i32 s48, s48, 0x51000
	s_add_u32 s5, s60, s48
	s_addc_u32 s4, s61, s4
	s_add_u32 s78, s5, 0x100000
	v_writelane_b32 v250, s82, 35
	s_addc_u32 s79, s4, 0
	v_readlane_b32 s20, v250, 20
	s_cmp_lg_u32 s20, 0
	s_cselect_b64 s[28:29], -1, 0
	s_add_u32 s30, s60, 0x1008
	s_addc_u32 s31, s61, 0
	s_add_u32 s34, s60, 0x1000
	s_addc_u32 s35, s61, 0
	s_mul_i32 s6, s82, 0x2400
	s_mul_hi_i32 s7, s82, 0x2400
	v_writelane_b32 v250, s80, 36
	s_and_b64 s[4:5], s[80:81], exec
	s_cselect_b32 s5, 0, s7
	s_cselect_b32 s4, 0, s6
	s_lshl_b64 s[4:5], s[4:5], 2
	s_add_u32 s4, s60, s4
	s_addc_u32 s5, s61, s5
	v_writelane_b32 v250, s81, 37
	s_add_u32 s80, s4, 0xc00000
	s_addc_u32 s81, s5, 0
	s_lshl_b32 s4, s20, 2
	s_add_i32 s4, s4, 0
	s_add_i32 s4, s4, 0x23fc8
	v_writelane_b32 v250, s4, 38
	s_add_u32 s4, s18, 0x1000
	v_add_u32_e32 v0, v17, v15
	s_addc_u32 s5, s19, 0
	v_add_lshl_u32 v0, v0, v16, 1
	v_mov_b32_e32 v1, v151
	s_waitcnt vmcnt(6)
	v_writelane_b32 v250, s4, 39
	v_lshl_add_u64 v[164:165], s[38:39], 0, v[0:1]
	v_add_u32_e32 v0, v14, v12
	v_lshlrev_b32_e32 v21, 3, v19
	v_writelane_b32 v250, s5, 40
	v_add_lshl_u32 v0, v0, v13, 1
	v_lshl_or_b32 v212, s70, 5, v21
	s_mov_b32 s49, 0
	v_mov_b32_e32 v160, v158
	v_mov_b32_e32 v161, v158
	v_cmp_eq_u32_e64 s[40:41], 0, v19
	v_lshl_add_u64 v[162:163], v[144:145], 2, s[18:19]
	v_lshl_add_u64 v[166:167], s[38:39], 0, v[0:1]
	v_add_u32_e32 v213, 0, v22
	v_readlane_b32 s48, v250, 11
	v_readlane_b32 s82, v250, 12
	s_barrier
	s_branch .LBB0_604
